# final norm_rows loop: dropped the dead copy-back moves left by the load hoist
# speedup vs baseline: 1.0011x; 1.0011x over previous
; __device__ __forceinline__ void norm_rows(CParams& p, int mode, const float* gain, int nrows) {
;     ...
;             for (int j = 0; j < 8; ++j) v[j] = *(const f32x4*)(H + (size_t)row * D + (lane + 64 * j) * 4);
;         }
;         float s = 0.f;
; #pragma unroll
;         for (int j = 0; j < 8; ++j) s += (v[j][0] * v[j][0] + v[j][1] * v[j][1]) + (v[j][2] * v[j][2] + v[j][3] * v[j][3]);
;         const float rs = 1.0f / sqrtf(wave_sum(s) * (1.0f / D) + EPS);
.LBB0_1463:
	v_lshl_add_u64 v[0:1], v[46:47], 0, v[32:33]
	global_load_dwordx4 v[28:31], v[0:1], off
	global_load_dwordx4 v[24:27], v[0:1], off offset:1024
	global_load_dwordx4 v[20:23], v[0:1], off offset:2048
	global_load_dwordx4 v[16:19], v[0:1], off offset:3072
	v_add_co_u32_e32 v70, vcc, 0x1000, v0
	s_nop 0
	v_addc_co_u32_e32 v71, vcc, 0, v1, vcc
	global_load_dwordx4 v[12:15], v[70:71], off
	global_load_dwordx4 v[8:11], v[70:71], off offset:1024
	global_load_dwordx4 v[4:7], v[70:71], off offset:2048
	global_load_dwordx4 v[0:3], v[70:71], off offset:3072
	global_load_dwordx4 v[120:123], v[36:37], off
	global_load_dwordx4 v[124:127], v[36:37], off offset:1024
	global_load_dwordx4 v[128:131], v[36:37], off offset:2048
	global_load_dwordx4 v[132:135], v[36:37], off offset:3072
	global_load_dwordx4 v[136:139], v[38:39], off
	global_load_dwordx4 v[140:143], v[40:41], off
	global_load_dwordx4 v[144:147], v[42:43], off
	global_load_dwordx4 v[148:151], v[44:45], off
	s_waitcnt vmcnt(0)
	v_add_u32_e32 v34, s50, v34
	v_lshl_add_u64 v[70:71], v[48:49], 0, v[32:33]
	v_lshl_add_u64 v[46:47], v[46:47], 0, s[20:21]
	v_lshl_add_u64 v[48:49], v[48:49], 0, s[20:21]
	v_mov_b32_e32 v74, v29
	v_mov_b32_e32 v75, v25
	v_mov_b32_e32 v78, v31
	v_mov_b32_e32 v79, v27
	v_mov_b32_e32 v72, v28
	v_mov_b32_e32 v73, v24
	v_mov_b32_e32 v76, v30
	v_mov_b32_e32 v77, v26
	v_pk_mul_f32 v[80:81], v[22:23], v[22:23]
	v_pk_mul_f32 v[82:83], v[20:21], v[20:21]
	v_pk_mul_f32 v[74:75], v[74:75], v[74:75]
	v_pk_mul_f32 v[78:79], v[78:79], v[78:79]
	v_pk_mov_b32 v[88:89], v[82:83], v[80:81] op_sel:[1,0]
	v_mov_b32_e32 v83, v81
	v_pk_fma_f32 v[72:73], v[72:73], v[72:73], v[74:75]
	v_pk_fma_f32 v[74:75], v[76:77], v[76:77], v[78:79]
	v_mul_f32_e32 v84, v17, v17
	v_mul_f32_e32 v86, v19, v19
	v_pk_add_f32 v[76:77], v[88:89], v[82:83]
	v_pk_add_f32 v[72:73], v[72:73], v[74:75]
	v_pk_fma_f32 v[80:81], v[16:17], v[16:17], v[84:85] op_sel_hi:[1,1,0]
	v_pk_fma_f32 v[84:85], v[18:19], v[18:19], v[86:87] op_sel_hi:[1,1,0]
	v_mul_f32_e32 v35, v12, v12
	v_mul_f32_e32 v65, v13, v13
	v_pk_add_f32 v[74:75], v[76:77], v[76:77] op_sel:[0,1] op_sel_hi:[1,0]
	v_pk_add_f32 v[72:73], v[72:73], v[72:73] op_sel:[0,1] op_sel_hi:[1,0]
	v_mul_f32_e32 v81, v14, v14
	v_mul_f32_e32 v85, v15, v15
	v_pk_mul_f32 v[78:79], v[10:11], v[10:11]
	v_pk_mul_f32 v[82:83], v[8:9], v[8:9]
	v_mov_b32_e32 v75, v65
	v_mov_b32_e32 v73, v35
	v_pk_mov_b32 v[76:77], v[82:83], v[78:79] op_sel:[1,0]
	v_mov_b32_e32 v83, v79
	v_pk_add_f32 v[80:81], v[80:81], v[84:85]
	v_pk_add_f32 v[72:73], v[72:73], v[74:75]
	v_mul_f32_e32 v89, v0, v0
	v_mul_f32_e32 v86, v5, v5
	v_mul_f32_e32 v88, v7, v7
	v_pk_add_f32 v[76:77], v[76:77], v[82:83]
	v_pk_add_f32 v[72:73], v[72:73], v[80:81]
	v_mul_f32_e32 v90, v1, v1
	v_mul_f32_e32 v91, v2, v2
	v_mul_f32_e32 v92, v3, v3
	v_pk_fma_f32 v[78:79], v[4:5], v[4:5], v[86:87] op_sel_hi:[1,1,0]
	v_pk_fma_f32 v[86:87], v[6:7], v[6:7], v[88:89] op_sel_hi:[1,1,0]
	v_pk_add_f32 v[76:77], v[76:77], v[76:77] op_sel:[0,1] op_sel_hi:[1,0]
	v_pk_add_f32 v[72:73], v[72:73], v[72:73] op_sel:[0,1] op_sel_hi:[1,0]
	v_mov_b32_e32 v79, v91
	v_mov_b32_e32 v87, v92
	v_mov_b32_e32 v77, v90
	v_mov_b32_e32 v73, v89
	v_pk_add_f32 v[78:79], v[78:79], v[86:87]
	v_pk_add_f32 v[72:73], v[72:73], v[76:77]
	s_nop 0
	v_pk_add_f32 v[72:73], v[72:73], v[78:79]
	s_nop 0
	v_add_f32_e32 v35, v72, v73
	ds_bpermute_b32 v65, v59, v35
	s_waitcnt lgkmcnt(0)
	v_add_f32_e32 v35, v35, v65
	ds_bpermute_b32 v65, v60, v35
	s_waitcnt lgkmcnt(0)
	v_add_f32_e32 v35, v35, v65
	ds_bpermute_b32 v65, v61, v35
	s_waitcnt lgkmcnt(0)
; __device__ __forceinline__ unsigned pk2(float lo, float hi) { const f32x2 v = {lo, hi}; const bf16v2 b = __builtin_convertvector(v, bf16v2); return __builtin_bit_cast(unsigned, b); }
; #define p (*kparams())
; __device__ __forceinline__ void norm_rows(CParams& p, int mode, const float* gain, int nrows) {
;     ...
;         const float rs = 1.0f / sqrtf(wave_sum(s) * (1.0f / D) + EPS);
; #pragma unroll
;         for (int j = 0; j < 8; ++j) {
;             const f32x4 g = *(const f32x4*)(gain + (lane + 64 * j) * 4);
;             const f32x4 y = v[j] * rs * g;
;             if (mode == 3) *(f32x4*)(p.out + (size_t)row * D + (lane + 64 * j) * 4) = y;
;             else { u32x2 w; w.x = pk2(y[0], y[1]); w.y = pk2(y[2], y[3]); *(u32x2*)(NB + (size_t)row * D + (lane + 64 * j) * 4) = w; }
;         }
	v_add_f32_e32 v35, v35, v65
	ds_bpermute_b32 v65, v62, v35
	s_waitcnt lgkmcnt(0)
	v_add_f32_e32 v35, v35, v65
	ds_bpermute_b32 v65, v63, v35
	s_waitcnt lgkmcnt(0)
	v_add_f32_e32 v35, v35, v65
	ds_bpermute_b32 v65, v64, v35
	s_waitcnt lgkmcnt(0)
	v_add_f32_e32 v35, v35, v65
	v_fmamk_f32 v35, v35, 0x3a000000, v50
	v_mul_f32_e32 v65, 0x4f800000, v35
	v_cmp_gt_f32_e32 vcc, s16, v35
	s_nop 1
	v_cndmask_b32_e32 v35, v35, v65, vcc
	v_sqrt_f32_e32 v65, v35
	s_nop 0
	v_add_u32_e32 v72, -1, v65
	v_add_u32_e32 v73, 1, v65
	v_fma_f32 v74, -v72, v65, v35
	v_fma_f32 v75, -v73, v65, v35
	v_cmp_ge_f32_e64 s[2:3], 0, v74
	s_nop 1
	v_cndmask_b32_e64 v65, v65, v72, s[2:3]
	v_cmp_lt_f32_e64 s[2:3], 0, v75
	s_nop 1
	v_cndmask_b32_e64 v65, v65, v73, s[2:3]
	v_mul_f32_e32 v72, 0x37800000, v65
	v_cndmask_b32_e32 v65, v65, v72, vcc
	v_cmp_class_f32_e32 vcc, v35, v51
	s_nop 1
	v_cndmask_b32_e32 v35, v65, v35, vcc
	v_div_scale_f32 v65, s[2:3], v35, v35, 1.0
	v_rcp_f32_e32 v73, v65
	v_div_scale_f32 v72, vcc, 1.0, v35, 1.0
	v_fma_f32 v74, -v65, v73, 1.0
	v_fmac_f32_e32 v73, v74, v73
	v_mul_f32_e32 v74, v72, v73
	v_fma_f32 v75, -v65, v74, v72
	v_fmac_f32_e32 v74, v75, v73
	v_fma_f32 v65, -v65, v74, v72
	v_div_fmas_f32 v65, v65, v73, v74
	v_div_fixup_f32 v72, v65, v35, 1.0
	v_pk_mul_f32 v[28:29], v[28:29], v[72:73] op_sel_hi:[1,0]
	v_pk_mul_f32 v[30:31], v[30:31], v[72:73] op_sel_hi:[1,0]
	v_pk_mul_f32 v[28:29], v[120:121], v[28:29]
	v_pk_mul_f32 v[30:31], v[122:123], v[30:31]
	global_store_dwordx4 v[70:71], v[28:31], off
	v_pk_mul_f32 v[26:27], v[26:27], v[72:73] op_sel_hi:[1,0]
	v_pk_mul_f32 v[24:25], v[24:25], v[72:73] op_sel_hi:[1,0]
	v_pk_mul_f32 v[22:23], v[22:23], v[72:73] op_sel_hi:[1,0]
	v_pk_mul_f32 v[20:21], v[20:21], v[72:73] op_sel_hi:[1,0]
	v_pk_mul_f32 v[18:19], v[18:19], v[72:73] op_sel_hi:[1,0]
	v_pk_mul_f32 v[16:17], v[16:17], v[72:73] op_sel_hi:[1,0]
	v_pk_mul_f32 v[14:15], v[14:15], v[72:73] op_sel_hi:[1,0]
	v_pk_mul_f32 v[12:13], v[12:13], v[72:73] op_sel_hi:[1,0]
	v_pk_mul_f32 v[10:11], v[10:11], v[72:73] op_sel_hi:[1,0]
	v_pk_mul_f32 v[8:9], v[8:9], v[72:73] op_sel_hi:[1,0]
	v_pk_mul_f32 v[6:7], v[6:7], v[72:73] op_sel_hi:[1,0]
	v_pk_mul_f32 v[4:5], v[4:5], v[72:73] op_sel_hi:[1,0]
	v_pk_mul_f32 v[2:3], v[2:3], v[72:73] op_sel_hi:[1,0]
	v_pk_mul_f32 v[0:1], v[0:1], v[72:73] op_sel_hi:[1,0]
	v_pk_mul_f32 v[24:25], v[124:125], v[24:25]
	v_pk_mul_f32 v[26:27], v[126:127], v[26:27]
	global_store_dwordx4 v[70:71], v[24:27], off offset:1024
	v_pk_mul_f32 v[20:21], v[128:129], v[20:21]
	v_pk_mul_f32 v[22:23], v[130:131], v[22:23]
	global_store_dwordx4 v[70:71], v[20:23], off offset:2048
	v_pk_mul_f32 v[16:17], v[132:133], v[16:17]
	v_pk_mul_f32 v[18:19], v[134:135], v[18:19]
	global_store_dwordx4 v[70:71], v[16:19], off offset:3072
	v_add_co_u32_e32 v20, vcc, s14, v70
	v_pk_mul_f32 v[12:13], v[136:137], v[12:13]
	v_addc_co_u32_e32 v21, vcc, 0, v71, vcc
	v_pk_mul_f32 v[14:15], v[138:139], v[14:15]
	global_store_dwordx4 v[20:21], v[12:15], off
	v_cmp_lt_i32_e32 vcc, s17, v34
	s_or_b64 s[4:5], vcc, s[4:5]
	v_pk_mul_f32 v[8:9], v[140:141], v[8:9]
	v_pk_mul_f32 v[10:11], v[142:143], v[10:11]
	global_store_dwordx4 v[20:21], v[8:11], off offset:1024
	v_pk_mul_f32 v[4:5], v[4:5], v[144:145]
	v_pk_mul_f32 v[6:7], v[6:7], v[146:147]
	global_store_dwordx4 v[20:21], v[4:7], off offset:2048
	v_pk_mul_f32 v[0:1], v[0:1], v[148:149]
	v_pk_mul_f32 v[2:3], v[2:3], v[150:151]
	global_store_dwordx4 v[20:21], v[0:3], off offset:3072
	s_andn2_b64 exec, exec, s[4:5]
	s_cbranch_execnz .LBB0_1463
	s_branch .LBB0_1460
